# mode-0 scan: b/kp operands stored transposed and read as lane%4 patterns four quads per ds_read_b128, LDS reads prefetched across the dot/update boundary and across steps
# speedup vs baseline: 1.0052x; 1.0052x over previous
; #define LAS __attribute__((address_space(3)))
; template <int MODE> __device__ __forceinline__ void rwkv_item(const Params& P, int e, int c, int h, LAS float* slab, int lane) {
;     unsigned char* ws = P.ws;
;     const bf16* PA = (const bf16*)(ws + OFF_PA);
;     const float* DEC = (const float*)(ws + OFF_DEC); const bf16* A16 = (const bf16*)(ws + OFF_A16); const bf16* G16 = (const bf16*)(ws + OFF_G16);
;     const bf16* V16 = (const bf16*)(ws + (e == 0 ? OFF_VF : OFF_V16));
;     float* MCM = (float*)(ws + OFF_MCM); float* MCC = (float*)(ws + OFF_MCC); bf16* MIX = (bf16*)(ws + OFF_MIXE);
;     const int ch = h * 64 + lane;
;     const float mu_r = P.in[I_AMU][(size_t)e * DINA + ch], mu_k = P.in[I_AMU][(size_t)e * DINA + 512 + ch];
;     const float kkw = P.in[I_AKK][e * 512 + ch], ka = P.in[I_AKA][e * 512 + ch], rk = P.in[I_ARK][e * 512 + ch];
;     const float lnw = P.in[I_ALNW][e * 512 + ch], lnb = P.in[I_ALNB][e * 512 + ch];
;     constexpr int SB = MODE == 0 ? 4 : 8;
;     f32x2 S2[32], C2[MODE == 0 ? 32 : 1];
;     const size_t rowoff = (((size_t)c * 8 + h) * 64 + lane) * 64;
; template <int MODE> __device__ __forceinline__ void stage_rwkv_scan(const Params& P, int e, LAS unsigned char* lds) {
;     int tid = threadIdx.x; asm volatile("" : "+v"(tid)); const int lane = tid & 63, wave = __builtin_amdgcn_readfirstlane(tid >> 6);
;     LAS float* slab = (LAS float*)(lds + wave * 16384);
;     const int gw = blockIdx.x * NWAVES + wave, ngw = gridDim.x * NWAVES;
;     for (int it = gw; it < RNCH * 8; it += ngw) rwkv_item<MODE>(P, e, it >> 3, it & 7, slab, lane);
.LBB0_254:
	s_and_b64 vcc, exec, s[0:1]
	s_cbranch_vccz .LBB0_273
	s_cmp_gt_i32 s67, 3
	s_mov_b64 s[0:1], -1
	s_cbranch_scc0 .LBB0_772
	v_readlane_b32 s0, v255, 6
	v_readlane_b32 s1, v255, 7
	s_cmp_gt_i32 s0, 0
	s_cselect_b64 s[0:1], -1, 0
	v_writelane_b32 v255, s0, 17
	s_cmp_lt_i32 s67, 6
	s_nop 0
	v_writelane_b32 v255, s1, 18
	s_mov_b64 s[0:1], -1
	s_cbranch_scc1 .LBB0_574
	s_cmp_lt_i32 s67, 7
	s_cbranch_scc1 .LBB0_372
	s_cmp_gt_i32 s67, 7
	s_cbranch_scc0 .LBB0_269
	v_readlane_b32 s0, v254, 63
	v_readlane_b32 s1, v255, 0
	s_andn2_b64 vcc, exec, s[0:1]
	s_cbranch_vccnz .LBB0_268
	v_mov_b32_e32 v0, v211
	s_nop 0
	v_readfirstlane_b32 s0, v0
	s_ashr_i32 s0, s0, 6
	s_add_i32 s20, s0, s55
	s_cmpk_gt_i32 s20, 0x7ff
	s_cbranch_scc1 .LBB0_268
	v_and_b32_e32 v128, 63, v0
	s_lshl_b32 s0, s0, 14
	s_add_i32 s21, s0, 0
	s_load_dwordx2 s[0:1], s[30:31], 0x38
	s_load_dwordx4 s[4:7], s[30:31], 0x68
	s_waitcnt lgkmcnt(0)
	s_add_u32 s8, s72, 0x12880000
	s_addc_u32 s9, s73, 0
	s_add_u32 s10, s72, 0xb880000
	s_addc_u32 s11, s73, 0
	v_readlane_b32 s2, v255, 5
	s_add_u32 s12, s0, s2
	v_readlane_b32 s0, v255, 4
	s_addc_u32 s13, s1, s0
	s_add_u32 s14, s72, 0xd880000
	s_addc_u32 s15, s73, 0
	v_readlane_b32 s0, v255, 3
	s_add_u32 s16, s72, s0
	s_addc_u32 s17, s73, 0
	s_add_u32 s18, s72, 0x10880000
	s_addc_u32 s19, s73, 0
	v_readlane_b32 s26, v254, 55
	v_readlane_b32 s27, v254, 56
	s_waitcnt vmcnt(0)
	v_lshl_add_u32 v129, v128, 2, s21
	v_and_b32_e32 v213, 3, v128
	v_lshrrev_b32_e32 v212, 2, v128
	v_lshl_add_u32 v212, v213, 4, v212
	v_lshl_add_u32 v212, v212, 2, s21
	v_lshl_add_u32 v213, v213, 6, s21

; #define LAS __attribute__((address_space(3)))
; __device__ __forceinline__ float frsq(float x) { return __builtin_amdgcn_rsqf(x); }
; template <int MODE> __device__ __forceinline__ void rwkv_item(const Params& P, int e, int c, int h, LAS float* slab, int lane) {
;     ...
;         for (int s = 0; s < SB; ++s) {
;             const float r = r1[s + 1] + (r1[s] - r1[s + 1]) * mu_r, k = k1[s + 1] + (k1[s] - k1[s + 1]) * mu_k, a = aa[s];
;             float kk = k * kkw;
;             const float ss = wave_sum(kk * kk);
;             kk *= frsq(fmaxf(ss, 1e-24f));
;             const float b = kk * a, kp = k * (1.f + (a - 1.f) * ka);
;             LAS float* st = slab + s * 512;
;             st[lane] = dd[s]; st[64 + lane] = kk; st[128 + lane] = b; st[192 + lane] = kp; st[256 + lane] = r; st[320 + lane] = vv[s];
;             if (MODE == 1) { st[384 + lane] = wave_sum(r * kp * rk); st[448 + lane] = gg[s]; }
;         }
.Lm0_sub:
	s_waitcnt vmcnt(0)
	v_lshlrev_b32_e32 v136, 16, v168
	v_sub_f32_e32 v130, v200, v136
	v_fma_f32 v130, v230, v130, v136
	v_mul_f32_e32 v131, v231, v130
	v_mul_f32_e32 v132, v131, v131
	v_lshlrev_b32_e32 v134, 16, v176
	v_lshlrev_b32_e32 v135, 16, v192
	v_mov_b32_dpp v132, v132 quad_perm:[1,0,3,2] row_mask:0xf bank_mask:0xf bound_ctrl:1
	v_fmac_f32_e32 v132, v131, v131
	v_mov_b32_e32 v200, v136
	s_nop 0
	v_add_f32_dpp v132, v132, v132 quad_perm:[2,3,0,1] row_mask:0xf bank_mask:0xf bound_ctrl:1
	s_nop 1
	v_add_f32_dpp v132, v132, v132 row_half_mirror row_mask:0xf bank_mask:0xf bound_ctrl:1
	s_nop 1
	v_add_f32_dpp v132, v132, v132 row_mirror row_mask:0xf bank_mask:0xf bound_ctrl:1
	s_nop 0
	v_readlane_b32 s3, v132, 16
	v_readlane_b32 s25, v132, 48
	v_readlane_b32 s2, v132, 0
	v_readlane_b32 s24, v132, 32
	v_mov_b32_e32 v132, s3
	v_mov_b32_e32 v133, s25
	v_add_f32_e32 v132, s2, v132
	v_add_f32_e32 v133, s24, v133
	v_add_f32_e32 v132, v132, v133
	v_max_f32_e32 v132, 0x179abe15, v132
	v_rsq_f32_e32 v132, v132
	v_add_f32_e32 v133, -1.0, v134
	v_fma_f32 v133, v232, v133, 1.0
	v_mul_f32_e32 v130, v130, v133
	v_mul_f32_e32 v131, v131, v132
	v_mul_f32_e32 v132, v131, v134
	v_mul_f32_e32 v131, v131, v137
	v_mul_f32_e32 v137, v137, v184
	v_rcp_f32_e32 v133, v137
	s_nop 0
	v_mul_f32_e32 v132, v132, v133
	v_mul_f32_e32 v130, v130, v133
	ds_write2st64_b32 v129, v131, v135 offset0:1 offset1:5
	ds_write2st64_b32 v212, v132, v130 offset0:2 offset1:3
	v_lshlrev_b32_e32 v136, 16, v169
	v_sub_f32_e32 v130, v200, v136
	v_fma_f32 v130, v230, v130, v136
	v_mul_f32_e32 v131, v231, v130
	v_mul_f32_e32 v132, v131, v131
	v_lshlrev_b32_e32 v134, 16, v177
	v_lshlrev_b32_e32 v135, 16, v193
	v_mov_b32_dpp v132, v132 quad_perm:[1,0,3,2] row_mask:0xf bank_mask:0xf bound_ctrl:1
	v_fmac_f32_e32 v132, v131, v131
	v_mov_b32_e32 v200, v136
	s_nop 0
	v_add_f32_dpp v132, v132, v132 quad_perm:[2,3,0,1] row_mask:0xf bank_mask:0xf bound_ctrl:1
	s_nop 1
	v_add_f32_dpp v132, v132, v132 row_half_mirror row_mask:0xf bank_mask:0xf bound_ctrl:1
	s_nop 1
	v_add_f32_dpp v132, v132, v132 row_mirror row_mask:0xf bank_mask:0xf bound_ctrl:1
	s_nop 0
	v_readlane_b32 s3, v132, 16
	v_readlane_b32 s25, v132, 48
	v_readlane_b32 s2, v132, 0
	v_readlane_b32 s24, v132, 32
	v_mov_b32_e32 v132, s3
	v_mov_b32_e32 v133, s25
	v_add_f32_e32 v132, s2, v132
	v_add_f32_e32 v133, s24, v133
	v_add_f32_e32 v132, v132, v133
	v_max_f32_e32 v132, 0x179abe15, v132
	v_rsq_f32_e32 v132, v132
	v_add_f32_e32 v133, -1.0, v134
	v_fma_f32 v133, v232, v133, 1.0
	v_mul_f32_e32 v130, v130, v133
	v_mul_f32_e32 v131, v131, v132
	v_mul_f32_e32 v132, v131, v134
	v_mul_f32_e32 v131, v131, v137
	v_mul_f32_e32 v137, v137, v185
	v_rcp_f32_e32 v133, v137
	s_nop 0
	v_mul_f32_e32 v132, v132, v133
	v_mul_f32_e32 v130, v130, v133
	ds_write2st64_b32 v129, v131, v135 offset0:9 offset1:13
	ds_write2st64_b32 v212, v132, v130 offset0:10 offset1:11
	v_lshlrev_b32_e32 v136, 16, v170
	v_sub_f32_e32 v130, v200, v136
	v_fma_f32 v130, v230, v130, v136
	v_mul_f32_e32 v131, v231, v130
	v_mul_f32_e32 v132, v131, v131
	v_lshlrev_b32_e32 v134, 16, v178
	v_lshlrev_b32_e32 v135, 16, v194
	v_mov_b32_dpp v132, v132 quad_perm:[1,0,3,2] row_mask:0xf bank_mask:0xf bound_ctrl:1
	v_fmac_f32_e32 v132, v131, v131
	v_mov_b32_e32 v200, v136
	s_nop 0
	v_add_f32_dpp v132, v132, v132 quad_perm:[2,3,0,1] row_mask:0xf bank_mask:0xf bound_ctrl:1
	s_nop 1
	v_add_f32_dpp v132, v132, v132 row_half_mirror row_mask:0xf bank_mask:0xf bound_ctrl:1
	s_nop 1
	v_add_f32_dpp v132, v132, v132 row_mirror row_mask:0xf bank_mask:0xf bound_ctrl:1
	s_nop 0
	v_readlane_b32 s3, v132, 16
	v_readlane_b32 s25, v132, 48
	v_readlane_b32 s2, v132, 0
	v_readlane_b32 s24, v132, 32
	v_mov_b32_e32 v132, s3
	v_mov_b32_e32 v133, s25
	v_add_f32_e32 v132, s2, v132
	v_add_f32_e32 v133, s24, v133
	v_add_f32_e32 v132, v132, v133
	v_max_f32_e32 v132, 0x179abe15, v132
	v_rsq_f32_e32 v132, v132
	v_add_f32_e32 v133, -1.0, v134
	v_fma_f32 v133, v232, v133, 1.0
	v_mul_f32_e32 v130, v130, v133
	v_mul_f32_e32 v131, v131, v132
	v_mul_f32_e32 v132, v131, v134
	v_mul_f32_e32 v131, v131, v137
	v_mul_f32_e32 v137, v137, v186
	v_rcp_f32_e32 v133, v137
	s_nop 0
	v_mul_f32_e32 v132, v132, v133
	v_mul_f32_e32 v130, v130, v133
	ds_write2st64_b32 v129, v131, v135 offset0:17 offset1:21
	ds_write2st64_b32 v212, v132, v130 offset0:18 offset1:19
	v_lshlrev_b32_e32 v136, 16, v171
	v_sub_f32_e32 v130, v200, v136
	v_fma_f32 v130, v230, v130, v136
	v_mul_f32_e32 v131, v231, v130
	v_mul_f32_e32 v132, v131, v131
	v_lshlrev_b32_e32 v134, 16, v179
	v_lshlrev_b32_e32 v135, 16, v195
	v_mov_b32_dpp v132, v132 quad_perm:[1,0,3,2] row_mask:0xf bank_mask:0xf bound_ctrl:1
	v_fmac_f32_e32 v132, v131, v131
	v_mov_b32_e32 v200, v136
	s_nop 0
	v_add_f32_dpp v132, v132, v132 quad_perm:[2,3,0,1] row_mask:0xf bank_mask:0xf bound_ctrl:1
	s_nop 1
	v_add_f32_dpp v132, v132, v132 row_half_mirror row_mask:0xf bank_mask:0xf bound_ctrl:1
	s_nop 1
	v_add_f32_dpp v132, v132, v132 row_mirror row_mask:0xf bank_mask:0xf bound_ctrl:1
	s_nop 0
	v_readlane_b32 s3, v132, 16
	v_readlane_b32 s25, v132, 48
	v_readlane_b32 s2, v132, 0
	v_readlane_b32 s24, v132, 32
	v_mov_b32_e32 v132, s3
	v_mov_b32_e32 v133, s25
	v_add_f32_e32 v132, s2, v132
	v_add_f32_e32 v133, s24, v133
	v_add_f32_e32 v132, v132, v133
	v_max_f32_e32 v132, 0x179abe15, v132
	v_rsq_f32_e32 v132, v132
	v_add_f32_e32 v133, -1.0, v134
	v_fma_f32 v133, v232, v133, 1.0
	v_mul_f32_e32 v130, v130, v133
	v_mul_f32_e32 v131, v131, v132
	v_mul_f32_e32 v132, v131, v134
	v_mul_f32_e32 v131, v131, v137
	v_mul_f32_e32 v137, v137, v187
	v_rcp_f32_e32 v133, v137
	s_nop 0
	v_mul_f32_e32 v132, v132, v133
; #define LAS __attribute__((address_space(3)))
; __device__ __forceinline__ float frsq(float x) { return __builtin_amdgcn_rsqf(x); }
; template <int MODE> __device__ __forceinline__ void rwkv_item(const Params& P, int e, int c, int h, LAS float* slab, int lane) {
;     ...
;         for (int s = 0; s < SB; ++s) {
;             const float r = r1[s + 1] + (r1[s] - r1[s + 1]) * mu_r, k = k1[s + 1] + (k1[s] - k1[s + 1]) * mu_k, a = aa[s];
;             float kk = k * kkw;
;             const float ss = wave_sum(kk * kk);
;             kk *= frsq(fmaxf(ss, 1e-24f));
;             const float b = kk * a, kp = k * (1.f + (a - 1.f) * ka);
;             LAS float* st = slab + s * 512;
;             st[lane] = dd[s]; st[64 + lane] = kk; st[128 + lane] = b; st[192 + lane] = kp; st[256 + lane] = r; st[320 + lane] = vv[s];
;             if (MODE == 1) { st[384 + lane] = wave_sum(r * kp * rk); st[448 + lane] = gg[s]; }
;         }
	v_mul_f32_e32 v130, v130, v133
	ds_write2st64_b32 v129, v131, v135 offset0:25 offset1:29
	ds_write2st64_b32 v212, v132, v130 offset0:26 offset1:27
	v_lshlrev_b32_e32 v136, 16, v172
	v_sub_f32_e32 v130, v200, v136
	v_fma_f32 v130, v230, v130, v136
	v_mul_f32_e32 v131, v231, v130
	v_mul_f32_e32 v132, v131, v131
	v_lshlrev_b32_e32 v134, 16, v180
	v_lshlrev_b32_e32 v135, 16, v196
	v_mov_b32_dpp v132, v132 quad_perm:[1,0,3,2] row_mask:0xf bank_mask:0xf bound_ctrl:1
	v_fmac_f32_e32 v132, v131, v131
	v_mov_b32_e32 v200, v136
	s_nop 0
	v_add_f32_dpp v132, v132, v132 quad_perm:[2,3,0,1] row_mask:0xf bank_mask:0xf bound_ctrl:1
	s_nop 1
	v_add_f32_dpp v132, v132, v132 row_half_mirror row_mask:0xf bank_mask:0xf bound_ctrl:1
	s_nop 1
	v_add_f32_dpp v132, v132, v132 row_mirror row_mask:0xf bank_mask:0xf bound_ctrl:1
	s_nop 0
	v_readlane_b32 s3, v132, 16
	v_readlane_b32 s25, v132, 48
	v_readlane_b32 s2, v132, 0
	v_readlane_b32 s24, v132, 32
	v_mov_b32_e32 v132, s3
	v_mov_b32_e32 v133, s25
	v_add_f32_e32 v132, s2, v132
	v_add_f32_e32 v133, s24, v133
	v_add_f32_e32 v132, v132, v133
	v_max_f32_e32 v132, 0x179abe15, v132
	v_rsq_f32_e32 v132, v132
	v_add_f32_e32 v133, -1.0, v134
	v_fma_f32 v133, v232, v133, 1.0
	v_mul_f32_e32 v130, v130, v133
	v_mul_f32_e32 v131, v131, v132
	v_mul_f32_e32 v132, v131, v134
	v_mul_f32_e32 v131, v131, v137
	v_mul_f32_e32 v137, v137, v188
	v_rcp_f32_e32 v133, v137
	s_nop 0
	v_mul_f32_e32 v132, v132, v133
	v_mul_f32_e32 v130, v130, v133
	ds_write2st64_b32 v129, v131, v135 offset0:33 offset1:37
	ds_write2st64_b32 v212, v132, v130 offset0:34 offset1:35
	v_lshlrev_b32_e32 v136, 16, v173
	v_sub_f32_e32 v130, v200, v136
	v_fma_f32 v130, v230, v130, v136
	v_mul_f32_e32 v131, v231, v130
	v_mul_f32_e32 v132, v131, v131
	v_lshlrev_b32_e32 v134, 16, v181
	v_lshlrev_b32_e32 v135, 16, v197
	v_mov_b32_dpp v132, v132 quad_perm:[1,0,3,2] row_mask:0xf bank_mask:0xf bound_ctrl:1
	v_fmac_f32_e32 v132, v131, v131
	v_mov_b32_e32 v200, v136
	s_nop 0
	v_add_f32_dpp v132, v132, v132 quad_perm:[2,3,0,1] row_mask:0xf bank_mask:0xf bound_ctrl:1
	s_nop 1
	v_add_f32_dpp v132, v132, v132 row_half_mirror row_mask:0xf bank_mask:0xf bound_ctrl:1
	s_nop 1
	v_add_f32_dpp v132, v132, v132 row_mirror row_mask:0xf bank_mask:0xf bound_ctrl:1
	s_nop 0
	v_readlane_b32 s3, v132, 16
	v_readlane_b32 s25, v132, 48
	v_readlane_b32 s2, v132, 0
	v_readlane_b32 s24, v132, 32
	v_mov_b32_e32 v132, s3
	v_mov_b32_e32 v133, s25
	v_add_f32_e32 v132, s2, v132
	v_add_f32_e32 v133, s24, v133
	v_add_f32_e32 v132, v132, v133
	v_max_f32_e32 v132, 0x179abe15, v132
	v_rsq_f32_e32 v132, v132
	v_add_f32_e32 v133, -1.0, v134
	v_fma_f32 v133, v232, v133, 1.0
	v_mul_f32_e32 v130, v130, v133
	v_mul_f32_e32 v131, v131, v132
	v_mul_f32_e32 v132, v131, v134
	v_mul_f32_e32 v131, v131, v137
	v_mul_f32_e32 v137, v137, v189
	v_rcp_f32_e32 v133, v137
	s_nop 0
	v_mul_f32_e32 v132, v132, v133
	v_mul_f32_e32 v130, v130, v133
	ds_write2st64_b32 v129, v131, v135 offset0:41 offset1:45
	ds_write2st64_b32 v212, v132, v130 offset0:42 offset1:43
	v_lshlrev_b32_e32 v136, 16, v174
	v_sub_f32_e32 v130, v200, v136
	v_fma_f32 v130, v230, v130, v136
	v_mul_f32_e32 v131, v231, v130
	v_mul_f32_e32 v132, v131, v131
	v_lshlrev_b32_e32 v134, 16, v182
	v_lshlrev_b32_e32 v135, 16, v198
	v_mov_b32_dpp v132, v132 quad_perm:[1,0,3,2] row_mask:0xf bank_mask:0xf bound_ctrl:1
	v_fmac_f32_e32 v132, v131, v131
	v_mov_b32_e32 v200, v136
	s_nop 0
	v_add_f32_dpp v132, v132, v132 quad_perm:[2,3,0,1] row_mask:0xf bank_mask:0xf bound_ctrl:1
	s_nop 1
	v_add_f32_dpp v132, v132, v132 row_half_mirror row_mask:0xf bank_mask:0xf bound_ctrl:1
	s_nop 1
	v_add_f32_dpp v132, v132, v132 row_mirror row_mask:0xf bank_mask:0xf bound_ctrl:1
	s_nop 0
	v_readlane_b32 s3, v132, 16
	v_readlane_b32 s25, v132, 48
	v_readlane_b32 s2, v132, 0
	v_readlane_b32 s24, v132, 32
	v_mov_b32_e32 v132, s3
	v_mov_b32_e32 v133, s25
	v_add_f32_e32 v132, s2, v132
	v_add_f32_e32 v133, s24, v133
	v_add_f32_e32 v132, v132, v133
	v_max_f32_e32 v132, 0x179abe15, v132
	v_rsq_f32_e32 v132, v132
	v_add_f32_e32 v133, -1.0, v134
	v_fma_f32 v133, v232, v133, 1.0
	v_mul_f32_e32 v130, v130, v133
	v_mul_f32_e32 v131, v131, v132
	v_mul_f32_e32 v132, v131, v134
	v_mul_f32_e32 v131, v131, v137
	v_mul_f32_e32 v137, v137, v190
	v_rcp_f32_e32 v133, v137
	s_nop 0
	v_mul_f32_e32 v132, v132, v133
	v_mul_f32_e32 v130, v130, v133
	ds_write2st64_b32 v129, v131, v135 offset0:49 offset1:53
	ds_write2st64_b32 v212, v132, v130 offset0:50 offset1:51
	v_lshlrev_b32_e32 v136, 16, v175
	v_sub_f32_e32 v130, v200, v136
	v_fma_f32 v130, v230, v130, v136
	v_mul_f32_e32 v131, v231, v130
	v_mul_f32_e32 v132, v131, v131
	v_lshlrev_b32_e32 v134, 16, v183
	v_lshlrev_b32_e32 v135, 16, v199
	v_mov_b32_dpp v132, v132 quad_perm:[1,0,3,2] row_mask:0xf bank_mask:0xf bound_ctrl:1
	v_fmac_f32_e32 v132, v131, v131
	v_mov_b32_e32 v200, v136
	s_nop 0
	v_add_f32_dpp v132, v132, v132 quad_perm:[2,3,0,1] row_mask:0xf bank_mask:0xf bound_ctrl:1
	s_nop 1
	v_add_f32_dpp v132, v132, v132 row_half_mirror row_mask:0xf bank_mask:0xf bound_ctrl:1
	s_nop 1
	v_add_f32_dpp v132, v132, v132 row_mirror row_mask:0xf bank_mask:0xf bound_ctrl:1
	s_nop 0
	v_readlane_b32 s3, v132, 16
	v_readlane_b32 s25, v132, 48
	v_readlane_b32 s2, v132, 0
	v_readlane_b32 s24, v132, 32
	v_mov_b32_e32 v132, s3
	v_mov_b32_e32 v133, s25
	v_add_f32_e32 v132, s2, v132
	v_add_f32_e32 v133, s24, v133
	v_add_f32_e32 v132, v132, v133
	v_max_f32_e32 v132, 0x179abe15, v132
	v_rsq_f32_e32 v132, v132
	v_add_f32_e32 v133, -1.0, v134
	v_fma_f32 v133, v232, v133, 1.0
	v_mul_f32_e32 v130, v130, v133
	v_mul_f32_e32 v131, v131, v132
	v_mul_f32_e32 v132, v131, v134
	v_mul_f32_e32 v131, v131, v137
	v_mul_f32_e32 v137, v137, v191
	v_rcp_f32_e32 v133, v137
	s_nop 0
	v_mul_f32_e32 v132, v132, v133
	v_mul_f32_e32 v130, v130, v133
	ds_write2st64_b32 v129, v131, v135 offset0:57 offset1:61
	ds_write2st64_b32 v212, v132, v130 offset0:58 offset1:59
	s_cmp_eq_u32 s23, 7
	s_cbranch_scc1 .Lm0_noload
; #define RW_LD_DOT(buf, hb) do { _Pragma("unroll") for (int q_ = 0; q_ < DB; ++q_) kd[buf][q_] = *(const LAS f32x4*)(st + 64 + 4 * (DB * (hb) + q_)); } while (0)
; #define RW_LD_UPD(buf, qb) do { _Pragma("unroll") for (int q_ = 0; q_ < UB; ++q_) { const int qq_ = UB * (qb) + q_; \
;                 wq[buf][q_] = *(const LAS f32x4*)(st + 4 * qq_); bq[buf][q_] = *(const LAS f32x4*)(st + 128 + 4 * qq_); kq[buf][q_] = *(const LAS f32x4*)(st + 192 + 4 * qq_); \
;                 if (MODE == 1) rq[buf][q_] = *(const LAS f32x4*)(st + 256 + 4 * qq_); } } while (0)
; template <int MODE> __device__ __forceinline__ void rwkv_item(const Params& P, int e, int c, int h, LAS float* slab, int lane) {
;     ...
;             if (NB == 2) RW_LD_DOT(0, 0);
;             const float v = st[320 + lane];
; #pragma unroll
;             for (int hb = 0; hb < NDB; ++hb) {
;                 if (NB == 2) { if (hb + 1 < NDB) RW_LD_DOT((hb + 1) & 1, hb + 1); else RW_LD_UPD(0, 0); } else RW_LD_DOT(0, hb);
;                 __builtin_amdgcn_sched_barrier(0);
; #pragma unroll
;                 for (int q = 0; q < DB; ++q) {
;                     const int qq = DB * hb + q; const f32x4 k4 = kd[hb & (NB - 1)][q];
;                     aS0 += S2[2 * qq] * (f32x2){k4.x, k4.y}; aS1 += S2[2 * qq + 1] * (f32x2){k4.z, k4.w};
;                     if (MODE == 0) { aC0 += C2[2 * qq] * (f32x2){k4.x, k4.y}; aC1 += C2[2 * qq + 1] * (f32x2){k4.z, k4.w}; }
;                 }
;                 __builtin_amdgcn_sched_barrier(0);
;             }
	global_load_ushort v168, v201, s[26:27]
	global_load_ushort v169, v201, s[26:27] offset:3584
	v_add_u32_e32 v204, 0x1c00, v201
	v_add_u32_e32 v205, 0x3800, v201
	v_add_u32_e32 v206, 0x5400, v201
	global_load_ushort v170, v204, s[26:27]
	global_load_ushort v171, v204, s[26:27] offset:3584
	global_load_ushort v172, v205, s[26:27]
	global_load_ushort v173, v205, s[26:27] offset:3584
	global_load_ushort v174, v206, s[26:27]
	global_load_ushort v175, v206, s[26:27] offset:3584
	v_add_u32_e32 v204, 0x1000, v202
	global_load_ushort v176, v202, s[14:15]
	global_load_ushort v177, v202, s[14:15] offset:1024
	global_load_ushort v178, v202, s[14:15] offset:2048
	global_load_ushort v179, v202, s[14:15] offset:3072
	global_load_ushort v180, v204, s[14:15]
	global_load_ushort v181, v204, s[14:15] offset:1024
	global_load_ushort v182, v204, s[14:15] offset:2048
	global_load_ushort v183, v204, s[14:15] offset:3072
	global_load_ushort v192, v202, s[16:17]
	global_load_ushort v193, v202, s[16:17] offset:1024
	global_load_ushort v194, v202, s[16:17] offset:2048
	global_load_ushort v195, v202, s[16:17] offset:3072
	global_load_ushort v196, v204, s[16:17]
	global_load_ushort v197, v204, s[16:17] offset:1024
	global_load_ushort v198, v204, s[16:17] offset:2048
	global_load_ushort v199, v204, s[16:17] offset:3072
	v_add_u32_e32 v205, 0x1000, v203
	v_add_u32_e32 v206, 0x2000, v203
	v_add_u32_e32 v207, 0x3000, v203
	global_load_dword v184, v203, s[10:11]
	global_load_dword v185, v203, s[10:11] offset:2048
	global_load_dword v186, v205, s[10:11]
	global_load_dword v187, v205, s[10:11] offset:2048
	global_load_dword v188, v206, s[10:11]
	global_load_dword v189, v206, s[10:11] offset:2048
	global_load_dword v190, v207, s[10:11]
	global_load_dword v191, v207, s[10:11] offset:2048
	v_add_u32_e32 v201, 0x7000, v201
	v_add_u32_e32 v202, 0x2000, v202
	v_add_u32_e32 v203, 0x4000, v203
.Lm0_noload:
	s_waitcnt lgkmcnt(0)
	s_mov_b32 s2, 0
	v_mov_b32_e32 v233, s21
	v_mov_b32_e32 v139, v213
	v_add_u32_e32 v138, 0x500, v129
	ds_read_b128 v[214:217], v233 offset:256
	ds_read_b128 v[234:237], v233 offset:272
	ds_read_b128 v[238:241], v233 offset:288
	ds_read_b128 v[242:245], v233 offset:304
	ds_read_b128 v[246:249], v233 offset:320
	s_waitcnt lgkmcnt(4)
	v_pk_fma_f32 v[158:159], v[112:113], v[214:215], 0 op_sel_hi:[1,1,0]
	v_pk_fma_f32 v[160:161], v[114:115], v[216:217], 0 op_sel_hi:[1,1,0]
	v_pk_fma_f32 v[162:163], v[124:125], v[214:215], 0 op_sel_hi:[1,1,0]
	v_pk_fma_f32 v[164:165], v[126:127], v[216:217], 0 op_sel_hi:[1,1,0]
	ds_read_b128 v[214:217], v233 offset:336
	s_waitcnt lgkmcnt(4)
	v_pk_fma_f32 v[158:159], v[104:105], v[234:235], v[158:159]
	v_pk_fma_f32 v[160:161], v[106:107], v[236:237], v[160:161]
	v_pk_fma_f32 v[162:163], v[120:121], v[234:235], v[162:163]
	v_pk_fma_f32 v[164:165], v[122:123], v[236:237], v[164:165]
	ds_read_b128 v[234:237], v233 offset:352
	s_waitcnt lgkmcnt(4)
	v_pk_fma_f32 v[158:159], v[92:93], v[238:239], v[158:159]
	v_pk_fma_f32 v[160:161], v[94:95], v[240:241], v[160:161]
	v_pk_fma_f32 v[162:163], v[116:117], v[238:239], v[162:163]
	v_pk_fma_f32 v[164:165], v[118:119], v[240:241], v[164:165]
	ds_read_b128 v[238:241], v233 offset:368
	s_waitcnt lgkmcnt(4)
	v_pk_fma_f32 v[158:159], v[76:77], v[242:243], v[158:159]
	v_pk_fma_f32 v[160:161], v[78:79], v[244:245], v[160:161]
	v_pk_fma_f32 v[162:163], v[108:109], v[242:243], v[162:163]
	v_pk_fma_f32 v[164:165], v[110:111], v[244:245], v[164:165]
	ds_read_b128 v[242:245], v233 offset:384
	s_waitcnt lgkmcnt(4)
	v_pk_fma_f32 v[158:159], v[64:65], v[246:247], v[158:159]
	v_pk_fma_f32 v[160:161], v[66:67], v[248:249], v[160:161]
	v_pk_fma_f32 v[162:163], v[96:97], v[246:247], v[162:163]
	v_pk_fma_f32 v[164:165], v[98:99], v[248:249], v[164:165]
	ds_read_b128 v[246:249], v233 offset:400
	s_waitcnt lgkmcnt(4)
	v_pk_fma_f32 v[158:159], v[100:101], v[214:215], v[158:159]
	v_pk_fma_f32 v[160:161], v[102:103], v[216:217], v[160:161]
	v_pk_fma_f32 v[162:163], v[80:81], v[214:215], v[162:163]
	v_pk_fma_f32 v[164:165], v[82:83], v[216:217], v[164:165]
	ds_read_b128 v[214:217], v233 offset:416
	s_waitcnt lgkmcnt(4)
	v_pk_fma_f32 v[158:159], v[88:89], v[234:235], v[158:159]
	v_pk_fma_f32 v[160:161], v[90:91], v[236:237], v[160:161]
	v_pk_fma_f32 v[162:163], v[68:69], v[234:235], v[162:163]
	v_pk_fma_f32 v[164:165], v[70:71], v[236:237], v[164:165]
	ds_read_b128 v[234:237], v233 offset:432
	s_waitcnt lgkmcnt(4)
	v_pk_fma_f32 v[158:159], v[84:85], v[238:239], v[158:159]
	v_pk_fma_f32 v[160:161], v[86:87], v[240:241], v[160:161]
	v_pk_fma_f32 v[162:163], v[52:53], v[238:239], v[162:163]
	v_pk_fma_f32 v[164:165], v[54:55], v[240:241], v[164:165]
	ds_read_b128 v[238:241], v233 offset:448
	s_waitcnt lgkmcnt(4)
	v_pk_fma_f32 v[158:159], v[72:73], v[242:243], v[158:159]
	v_pk_fma_f32 v[160:161], v[74:75], v[244:245], v[160:161]
	v_pk_fma_f32 v[162:163], v[44:45], v[242:243], v[162:163]
	v_pk_fma_f32 v[164:165], v[46:47], v[244:245], v[164:165]
	ds_read_b128 v[242:245], v233 offset:464
	s_waitcnt lgkmcnt(4)
	v_pk_fma_f32 v[158:159], v[60:61], v[246:247], v[158:159]
	v_pk_fma_f32 v[160:161], v[62:63], v[248:249], v[160:161]
	v_pk_fma_f32 v[162:163], v[32:33], v[246:247], v[162:163]
	v_pk_fma_f32 v[164:165], v[34:35], v[248:249], v[164:165]
	ds_read_b128 v[246:249], v233 offset:480
	s_waitcnt lgkmcnt(4)
	v_pk_fma_f32 v[158:159], v[56:57], v[214:215], v[158:159]
	v_pk_fma_f32 v[160:161], v[58:59], v[216:217], v[160:161]
	v_pk_fma_f32 v[162:163], v[24:25], v[214:215], v[162:163]
	v_pk_fma_f32 v[164:165], v[26:27], v[216:217], v[164:165]
	ds_read_b128 v[214:217], v233 offset:496
	s_waitcnt lgkmcnt(4)
	v_pk_fma_f32 v[158:159], v[48:49], v[234:235], v[158:159]
	v_pk_fma_f32 v[160:161], v[50:51], v[236:237], v[160:161]
	v_pk_fma_f32 v[162:163], v[16:17], v[234:235], v[162:163]
	v_pk_fma_f32 v[164:165], v[18:19], v[236:237], v[164:165]
	s_waitcnt lgkmcnt(3)
	v_pk_fma_f32 v[158:159], v[40:41], v[238:239], v[158:159]
	v_pk_fma_f32 v[160:161], v[42:43], v[240:241], v[160:161]
	v_pk_fma_f32 v[162:163], v[12:13], v[238:239], v[162:163]
	v_pk_fma_f32 v[164:165], v[14:15], v[240:241], v[164:165]
	s_waitcnt lgkmcnt(2)
	v_pk_fma_f32 v[158:159], v[36:37], v[242:243], v[158:159]
	v_pk_fma_f32 v[160:161], v[38:39], v[244:245], v[160:161]
	v_pk_fma_f32 v[162:163], v[8:9], v[242:243], v[162:163]
	v_pk_fma_f32 v[164:165], v[10:11], v[244:245], v[164:165]
	s_waitcnt lgkmcnt(1)
	v_pk_fma_f32 v[158:159], v[28:29], v[246:247], v[158:159]
	v_pk_fma_f32 v[160:161], v[30:31], v[248:249], v[160:161]
	v_pk_fma_f32 v[162:163], v[4:5], v[246:247], v[162:163]
	v_pk_fma_f32 v[164:165], v[6:7], v[248:249], v[164:165]
	s_waitcnt lgkmcnt(0)
	v_pk_fma_f32 v[158:159], v[20:21], v[214:215], v[158:159]
	v_pk_fma_f32 v[160:161], v[22:23], v[216:217], v[160:161]
	v_pk_fma_f32 v[162:163], v[0:1], v[214:215], v[162:163]
	v_pk_fma_f32 v[164:165], v[2:3], v[216:217], v[164:165]
	ds_read_b32 v136, v138
	ds_read_b128 v[140:143], v139 offset:512
	ds_read_b128 v[130:133], v139 offset:768
; template <int MODE> __device__ __forceinline__ void rwkv_item(const Params& P, int e, int c, int h, LAS float* slab, int lane) {
;     ...
;             for (int hb = 0; hb < NDB; ++hb) {
;                 if (NB == 2) { if (hb + 1 < NDB) RW_LD_DOT((hb + 1) & 1, hb + 1); else RW_LD_UPD(0, 0); } else RW_LD_DOT(0, hb);
;                 __builtin_amdgcn_sched_barrier(0);
; #pragma unroll
;                 for (int q = 0; q < DB; ++q) {
;                     const int qq = DB * hb + q; const f32x4 k4 = kd[hb & (NB - 1)][q];
;                     aS0 += S2[2 * qq] * (f32x2){k4.x, k4.y}; aS1 += S2[2 * qq + 1] * (f32x2){k4.z, k4.w};
;                     if (MODE == 0) { aC0 += C2[2 * qq] * (f32x2){k4.x, k4.y}; aC1 += C2[2 * qq + 1] * (f32x2){k4.z, k4.w}; }
;                 }
;                 __builtin_amdgcn_sched_barrier(0);
;             }
;             const float nsk = -((aS0.x + aS0.y) + (aS1.x + aS1.y));
;             const float nskC = -((aC0.x + aC0.y) + (aC1.x + aC1.y));
;             f32x2 y0 = {0.f, 0.f}, y1 = {0.f, 0.f};
; #pragma unroll
;             for (int qb = 0; qb < NUB; ++qb) {
;                 if (NB == 2) { if (qb + 1 < NUB) RW_LD_UPD((qb + 1) & 1, qb + 1); } else RW_LD_UPD(0, qb);
;                 __builtin_amdgcn_sched_barrier(0);
; #pragma unroll
;                 for (int q = 0; q < UB; ++q) {
;                     const int qq = UB * qb + q;
;                     const f32x4 w4 = wq[qb & (NB - 1)][q], b4 = bq[qb & (NB - 1)][q], k4 = kq[qb & (NB - 1)][q];
;                     if (MODE == 0) {
;                         S2[2 * qq] = S2[2 * qq] * (f32x2){w4.x, w4.y} + (f32x2){b4.x, b4.y} * nsk;
;                         S2[2 * qq + 1] = S2[2 * qq + 1] * (f32x2){w4.z, w4.w} + (f32x2){b4.z, b4.w} * nsk;
;                         C2[2 * qq] = C2[2 * qq] * (f32x2){w4.x, w4.y} + (f32x2){b4.x, b4.y} * nskC + (f32x2){k4.x, k4.y} * v;
;                         C2[2 * qq + 1] = C2[2 * qq + 1] * (f32x2){w4.z, w4.w} + (f32x2){b4.z, b4.w} * nskC + (f32x2){k4.z, k4.w} * v;
;                     } else {
;                         S2[2 * qq] = S2[2 * qq] * (f32x2){w4.x, w4.y} + (f32x2){b4.x, b4.y} * nsk + (f32x2){k4.x, k4.y} * v;
;                         S2[2 * qq + 1] = S2[2 * qq + 1] * (f32x2){w4.z, w4.w} + (f32x2){b4.z, b4.w} * nsk + (f32x2){k4.z, k4.w} * v;
.Lm0_step:
	v_add_f32_e32 v208, v158, v159
	v_add_f32_e32 v209, v160, v161
	v_add_f32_e32 v250, v162, v163
	v_add_f32_e32 v251, v164, v165
	ds_read_b128 v[144:147], v139 offset:528
	ds_read_b128 v[148:151], v139 offset:784
	ds_read_b128 v[214:217], v233 offset:2304
	ds_read_b128 v[234:237], v233 offset:2320
	ds_read_b128 v[238:241], v233 offset:2336
	ds_read_b128 v[242:245], v233 offset:2352
	ds_read_b128 v[246:249], v233 offset:2368
	v_sub_f32_e64 v208, -v209, v208
	v_sub_f32_e64 v250, -v251, v250
	s_waitcnt lgkmcnt(9)
	v_mov_b32_e32 v152, v136
	s_nop 0
	s_waitcnt lgkmcnt(8)
	v_mfma_f32_4x4x1_16b_f32 v[112:115], v140, v208, v[112:115]
	v_mfma_f32_4x4x1_16b_f32 v[124:127], v140, v250, v[124:127]
	v_mfma_f32_4x4x1_16b_f32 v[104:107], v141, v208, v[104:107]
	v_mfma_f32_4x4x1_16b_f32 v[120:123], v141, v250, v[120:123]
	s_waitcnt lgkmcnt(7)
	v_mfma_f32_4x4x1_16b_f32 v[124:127], v130, v152, v[124:127]
	v_mfma_f32_4x4x1_16b_f32 v[92:95], v142, v208, v[92:95]
	v_mfma_f32_4x4x1_16b_f32 v[116:119], v142, v250, v[116:119]
	v_mfma_f32_4x4x1_16b_f32 v[120:123], v131, v152, v[120:123]
	v_mfma_f32_4x4x1_16b_f32 v[76:79], v143, v208, v[76:79]
	v_mfma_f32_4x4x1_16b_f32 v[108:111], v143, v250, v[108:111]
	v_mfma_f32_4x4x1_16b_f32 v[116:119], v132, v152, v[116:119]
	ds_read_b128 v[140:143], v139 offset:544
	s_waitcnt lgkmcnt(7)
	v_mfma_f32_4x4x1_16b_f32 v[64:67], v144, v208, v[64:67]
	v_mfma_f32_4x4x1_16b_f32 v[96:99], v144, v250, v[96:99]
	v_mfma_f32_4x4x1_16b_f32 v[108:111], v133, v152, v[108:111]
	ds_read_b128 v[130:133], v139 offset:800
	v_mfma_f32_4x4x1_16b_f32 v[100:103], v145, v208, v[100:103]
	v_mfma_f32_4x4x1_16b_f32 v[80:83], v145, v250, v[80:83]
	s_waitcnt lgkmcnt(7)
	v_mfma_f32_4x4x1_16b_f32 v[96:99], v148, v152, v[96:99]
	v_mfma_f32_4x4x1_16b_f32 v[88:91], v146, v208, v[88:91]
	v_mfma_f32_4x4x1_16b_f32 v[68:71], v146, v250, v[68:71]
	v_mfma_f32_4x4x1_16b_f32 v[80:83], v149, v152, v[80:83]
	v_mfma_f32_4x4x1_16b_f32 v[84:87], v147, v208, v[84:87]
	v_mfma_f32_4x4x1_16b_f32 v[52:55], v147, v250, v[52:55]
	v_mfma_f32_4x4x1_16b_f32 v[68:71], v150, v152, v[68:71]
	ds_read_b128 v[144:147], v139 offset:560
	s_waitcnt lgkmcnt(2)
	v_mfma_f32_4x4x1_16b_f32 v[72:75], v140, v208, v[72:75]
	v_mfma_f32_4x4x1_16b_f32 v[44:47], v140, v250, v[44:47]
	v_mfma_f32_4x4x1_16b_f32 v[52:55], v151, v152, v[52:55]
	ds_read_b128 v[148:151], v139 offset:816
	v_mfma_f32_4x4x1_16b_f32 v[60:63], v141, v208, v[60:63]
	v_mfma_f32_4x4x1_16b_f32 v[32:35], v141, v250, v[32:35]
	s_waitcnt lgkmcnt(2)
	v_mfma_f32_4x4x1_16b_f32 v[44:47], v130, v152, v[44:47]
	v_mfma_f32_4x4x1_16b_f32 v[56:59], v142, v208, v[56:59]
	v_mfma_f32_4x4x1_16b_f32 v[24:27], v142, v250, v[24:27]
	v_mfma_f32_4x4x1_16b_f32 v[32:35], v131, v152, v[32:35]
	v_mfma_f32_4x4x1_16b_f32 v[48:51], v143, v208, v[48:51]
	v_mfma_f32_4x4x1_16b_f32 v[16:19], v143, v250, v[16:19]
	v_mfma_f32_4x4x1_16b_f32 v[24:27], v132, v152, v[24:27]
	s_waitcnt lgkmcnt(1)
	v_mfma_f32_4x4x1_16b_f32 v[40:43], v144, v208, v[40:43]
	v_mfma_f32_4x4x1_16b_f32 v[12:15], v144, v250, v[12:15]
	v_mfma_f32_4x4x1_16b_f32 v[16:19], v133, v152, v[16:19]
	v_mfma_f32_4x4x1_16b_f32 v[36:39], v145, v208, v[36:39]
	v_mfma_f32_4x4x1_16b_f32 v[8:11], v145, v250, v[8:11]
	s_waitcnt lgkmcnt(0)
	v_mfma_f32_4x4x1_16b_f32 v[12:15], v148, v152, v[12:15]
	v_mfma_f32_4x4x1_16b_f32 v[28:31], v146, v208, v[28:31]
	v_mfma_f32_4x4x1_16b_f32 v[4:7], v146, v250, v[4:7]
	v_mfma_f32_4x4x1_16b_f32 v[8:11], v149, v152, v[8:11]
	v_mfma_f32_4x4x1_16b_f32 v[20:23], v147, v208, v[20:23]
	v_mfma_f32_4x4x1_16b_f32 v[0:3], v147, v250, v[0:3]
	v_mfma_f32_4x4x1_16b_f32 v[4:7], v150, v152, v[4:7]
	s_nop 0
	v_mfma_f32_4x4x1_16b_f32 v[0:3], v151, v152, v[0:3]
	s_waitcnt lgkmcnt(8)
	v_pk_fma_f32 v[158:159], v[112:113], v[214:215], 0 op_sel_hi:[1,1,0]
	v_pk_fma_f32 v[160:161], v[114:115], v[216:217], 0 op_sel_hi:[1,1,0]
	v_pk_fma_f32 v[162:163], v[124:125], v[214:215], 0 op_sel_hi:[1,1,0]
	v_pk_fma_f32 v[164:165], v[126:127], v[216:217], 0 op_sel_hi:[1,1,0]
	ds_read_b128 v[214:217], v233 offset:2384
	s_waitcnt lgkmcnt(8)
	v_pk_fma_f32 v[158:159], v[104:105], v[234:235], v[158:159]
	v_pk_fma_f32 v[160:161], v[106:107], v[236:237], v[160:161]
	v_pk_fma_f32 v[162:163], v[120:121], v[234:235], v[162:163]
	v_pk_fma_f32 v[164:165], v[122:123], v[236:237], v[164:165]
	ds_read_b128 v[234:237], v233 offset:2400
	s_waitcnt lgkmcnt(8)
	v_pk_fma_f32 v[158:159], v[92:93], v[238:239], v[158:159]
	v_pk_fma_f32 v[160:161], v[94:95], v[240:241], v[160:161]
	v_pk_fma_f32 v[162:163], v[116:117], v[238:239], v[162:163]
	v_pk_fma_f32 v[164:165], v[118:119], v[240:241], v[164:165]
	ds_read_b128 v[238:241], v233 offset:2416
	s_waitcnt lgkmcnt(8)
	v_pk_fma_f32 v[158:159], v[76:77], v[242:243], v[158:159]
	v_pk_fma_f32 v[160:161], v[78:79], v[244:245], v[160:161]
	v_pk_fma_f32 v[162:163], v[108:109], v[242:243], v[162:163]
	v_pk_fma_f32 v[164:165], v[110:111], v[244:245], v[164:165]
	ds_read_b128 v[242:245], v233 offset:2432
	s_waitcnt lgkmcnt(8)
	v_pk_fma_f32 v[158:159], v[64:65], v[246:247], v[158:159]
	v_pk_fma_f32 v[160:161], v[66:67], v[248:249], v[160:161]
	v_pk_fma_f32 v[162:163], v[96:97], v[246:247], v[162:163]
	v_pk_fma_f32 v[164:165], v[98:99], v[248:249], v[164:165]
	ds_read_b128 v[246:249], v233 offset:2448
	s_waitcnt lgkmcnt(4)
	v_pk_fma_f32 v[158:159], v[100:101], v[214:215], v[158:159]
	v_pk_fma_f32 v[160:161], v[102:103], v[216:217], v[160:161]
	v_pk_fma_f32 v[162:163], v[80:81], v[214:215], v[162:163]
	v_pk_fma_f32 v[164:165], v[82:83], v[216:217], v[164:165]
	ds_read_b128 v[214:217], v233 offset:2464
	s_waitcnt lgkmcnt(4)
; template <int MODE> __device__ __forceinline__ void rwkv_item(const Params& P, int e, int c, int h, LAS float* slab, int lane) {
;     ...
;             for (int hb = 0; hb < NDB; ++hb) {
;                 if (NB == 2) { if (hb + 1 < NDB) RW_LD_DOT((hb + 1) & 1, hb + 1); else RW_LD_UPD(0, 0); } else RW_LD_DOT(0, hb);
;                 __builtin_amdgcn_sched_barrier(0);
; #pragma unroll
;                 for (int q = 0; q < DB; ++q) {
;                     const int qq = DB * hb + q; const f32x4 k4 = kd[hb & (NB - 1)][q];
;                     aS0 += S2[2 * qq] * (f32x2){k4.x, k4.y}; aS1 += S2[2 * qq + 1] * (f32x2){k4.z, k4.w};
;                     if (MODE == 0) { aC0 += C2[2 * qq] * (f32x2){k4.x, k4.y}; aC1 += C2[2 * qq + 1] * (f32x2){k4.z, k4.w}; }
;                 }
;                 __builtin_amdgcn_sched_barrier(0);
;             }
;             const float nsk = -((aS0.x + aS0.y) + (aS1.x + aS1.y));
;             const float nskC = -((aC0.x + aC0.y) + (aC1.x + aC1.y));
;             f32x2 y0 = {0.f, 0.f}, y1 = {0.f, 0.f};
; #pragma unroll
;             for (int qb = 0; qb < NUB; ++qb) {
;                 if (NB == 2) { if (qb + 1 < NUB) RW_LD_UPD((qb + 1) & 1, qb + 1); } else RW_LD_UPD(0, qb);
;                 __builtin_amdgcn_sched_barrier(0);
; #pragma unroll
;                 for (int q = 0; q < UB; ++q) {
;                     const int qq = UB * qb + q;
;                     const f32x4 w4 = wq[qb & (NB - 1)][q], b4 = bq[qb & (NB - 1)][q], k4 = kq[qb & (NB - 1)][q];
;                     if (MODE == 0) {
;                         S2[2 * qq] = S2[2 * qq] * (f32x2){w4.x, w4.y} + (f32x2){b4.x, b4.y} * nsk;
;                         S2[2 * qq + 1] = S2[2 * qq + 1] * (f32x2){w4.z, w4.w} + (f32x2){b4.z, b4.w} * nsk;
;                         C2[2 * qq] = C2[2 * qq] * (f32x2){w4.x, w4.y} + (f32x2){b4.x, b4.y} * nskC + (f32x2){k4.x, k4.y} * v;
;                         C2[2 * qq + 1] = C2[2 * qq + 1] * (f32x2){w4.z, w4.w} + (f32x2){b4.z, b4.w} * nskC + (f32x2){k4.z, k4.w} * v;
;                     } else {
;                         S2[2 * qq] = S2[2 * qq] * (f32x2){w4.x, w4.y} + (f32x2){b4.x, b4.y} * nsk + (f32x2){k4.x, k4.y} * v;
;                         S2[2 * qq + 1] = S2[2 * qq + 1] * (f32x2){w4.z, w4.w} + (f32x2){b4.z, b4.w} * nsk + (f32x2){k4.z, k4.w} * v;
	v_pk_fma_f32 v[158:159], v[88:89], v[234:235], v[158:159]
	v_pk_fma_f32 v[160:161], v[90:91], v[236:237], v[160:161]
	v_pk_fma_f32 v[162:163], v[68:69], v[234:235], v[162:163]
	v_pk_fma_f32 v[164:165], v[70:71], v[236:237], v[164:165]
	ds_read_b128 v[234:237], v233 offset:2480
	s_waitcnt lgkmcnt(4)
	v_pk_fma_f32 v[158:159], v[84:85], v[238:239], v[158:159]
	v_pk_fma_f32 v[160:161], v[86:87], v[240:241], v[160:161]
	v_pk_fma_f32 v[162:163], v[52:53], v[238:239], v[162:163]
	v_pk_fma_f32 v[164:165], v[54:55], v[240:241], v[164:165]
	ds_read_b128 v[238:241], v233 offset:2496
	s_waitcnt lgkmcnt(4)
	v_pk_fma_f32 v[158:159], v[72:73], v[242:243], v[158:159]
	v_pk_fma_f32 v[160:161], v[74:75], v[244:245], v[160:161]
	v_pk_fma_f32 v[162:163], v[44:45], v[242:243], v[162:163]
	v_pk_fma_f32 v[164:165], v[46:47], v[244:245], v[164:165]
	ds_read_b128 v[242:245], v233 offset:2512
	s_waitcnt lgkmcnt(4)
	v_pk_fma_f32 v[158:159], v[60:61], v[246:247], v[158:159]
	v_pk_fma_f32 v[160:161], v[62:63], v[248:249], v[160:161]
	v_pk_fma_f32 v[162:163], v[32:33], v[246:247], v[162:163]
	v_pk_fma_f32 v[164:165], v[34:35], v[248:249], v[164:165]
	ds_read_b128 v[246:249], v233 offset:2528
	s_waitcnt lgkmcnt(4)
	v_pk_fma_f32 v[158:159], v[56:57], v[214:215], v[158:159]
	v_pk_fma_f32 v[160:161], v[58:59], v[216:217], v[160:161]
	v_pk_fma_f32 v[162:163], v[24:25], v[214:215], v[162:163]
	v_pk_fma_f32 v[164:165], v[26:27], v[216:217], v[164:165]
	ds_read_b128 v[214:217], v233 offset:2544
	ds_read_b32 v136, v138 offset:2048
	ds_read_b128 v[140:143], v139 offset:2560
	ds_read_b128 v[130:133], v139 offset:2816
	s_waitcnt lgkmcnt(7)
	v_pk_fma_f32 v[158:159], v[48:49], v[234:235], v[158:159]
	v_pk_fma_f32 v[160:161], v[50:51], v[236:237], v[160:161]
	v_pk_fma_f32 v[162:163], v[16:17], v[234:235], v[162:163]
	v_pk_fma_f32 v[164:165], v[18:19], v[236:237], v[164:165]
	s_waitcnt lgkmcnt(6)
	v_pk_fma_f32 v[158:159], v[40:41], v[238:239], v[158:159]
	v_pk_fma_f32 v[160:161], v[42:43], v[240:241], v[160:161]
	v_pk_fma_f32 v[162:163], v[12:13], v[238:239], v[162:163]
	v_pk_fma_f32 v[164:165], v[14:15], v[240:241], v[164:165]
	s_waitcnt lgkmcnt(5)
	v_pk_fma_f32 v[158:159], v[36:37], v[242:243], v[158:159]
	v_pk_fma_f32 v[160:161], v[38:39], v[244:245], v[160:161]
	v_pk_fma_f32 v[162:163], v[8:9], v[242:243], v[162:163]
	v_pk_fma_f32 v[164:165], v[10:11], v[244:245], v[164:165]
	s_waitcnt lgkmcnt(4)
	v_pk_fma_f32 v[158:159], v[28:29], v[246:247], v[158:159]
	v_pk_fma_f32 v[160:161], v[30:31], v[248:249], v[160:161]
	v_pk_fma_f32 v[162:163], v[4:5], v[246:247], v[162:163]
	v_pk_fma_f32 v[164:165], v[6:7], v[248:249], v[164:165]
	s_waitcnt lgkmcnt(3)
	v_pk_fma_f32 v[158:159], v[20:21], v[214:215], v[158:159]
	v_pk_fma_f32 v[160:161], v[22:23], v[216:217], v[160:161]
	v_pk_fma_f32 v[162:163], v[0:1], v[214:215], v[162:163]
	v_pk_fma_f32 v[164:165], v[2:3], v[216:217], v[164:165]
	v_add_u32_e32 v233, 0x800, v233
	v_add_u32_e32 v139, 0x800, v139
	v_add_u32_e32 v138, 0x800, v138
	s_addk_i32 s2, 0x800
	s_cmpk_eq_i32 s2, 0x3800
	s_cbranch_scc0 .Lm0_step
.Lm0_tail:
	v_add_f32_e32 v208, v158, v159
	v_add_f32_e32 v209, v160, v161
	v_add_f32_e32 v250, v162, v163
	v_add_f32_e32 v251, v164, v165
	ds_read_b128 v[144:147], v139 offset:528
	ds_read_b128 v[148:151], v139 offset:784
	v_sub_f32_e64 v208, -v209, v208
	v_sub_f32_e64 v250, -v251, v250
	s_waitcnt lgkmcnt(4)
	v_mov_b32_e32 v152, v136
	s_nop 0
	s_waitcnt lgkmcnt(3)
	v_mfma_f32_4x4x1_16b_f32 v[112:115], v140, v208, v[112:115]
	v_mfma_f32_4x4x1_16b_f32 v[124:127], v140, v250, v[124:127]
	v_mfma_f32_4x4x1_16b_f32 v[104:107], v141, v208, v[104:107]
	v_mfma_f32_4x4x1_16b_f32 v[120:123], v141, v250, v[120:123]
	s_waitcnt lgkmcnt(2)
	v_mfma_f32_4x4x1_16b_f32 v[124:127], v130, v152, v[124:127]
	v_mfma_f32_4x4x1_16b_f32 v[92:95], v142, v208, v[92:95]
	v_mfma_f32_4x4x1_16b_f32 v[116:119], v142, v250, v[116:119]
	v_mfma_f32_4x4x1_16b_f32 v[120:123], v131, v152, v[120:123]
	v_mfma_f32_4x4x1_16b_f32 v[76:79], v143, v208, v[76:79]
	v_mfma_f32_4x4x1_16b_f32 v[108:111], v143, v250, v[108:111]
	v_mfma_f32_4x4x1_16b_f32 v[116:119], v132, v152, v[116:119]
	ds_read_b128 v[140:143], v139 offset:544
	s_waitcnt lgkmcnt(2)
	v_mfma_f32_4x4x1_16b_f32 v[64:67], v144, v208, v[64:67]
	v_mfma_f32_4x4x1_16b_f32 v[96:99], v144, v250, v[96:99]
	v_mfma_f32_4x4x1_16b_f32 v[108:111], v133, v152, v[108:111]
	ds_read_b128 v[130:133], v139 offset:800
	v_mfma_f32_4x4x1_16b_f32 v[100:103], v145, v208, v[100:103]
	v_mfma_f32_4x4x1_16b_f32 v[80:83], v145, v250, v[80:83]
	s_waitcnt lgkmcnt(2)
	v_mfma_f32_4x4x1_16b_f32 v[96:99], v148, v152, v[96:99]
	v_mfma_f32_4x4x1_16b_f32 v[88:91], v146, v208, v[88:91]
	v_mfma_f32_4x4x1_16b_f32 v[68:71], v146, v250, v[68:71]
	v_mfma_f32_4x4x1_16b_f32 v[80:83], v149, v152, v[80:83]
	v_mfma_f32_4x4x1_16b_f32 v[84:87], v147, v208, v[84:87]
	v_mfma_f32_4x4x1_16b_f32 v[52:55], v147, v250, v[52:55]
	v_mfma_f32_4x4x1_16b_f32 v[68:71], v150, v152, v[68:71]
	ds_read_b128 v[144:147], v139 offset:560
	s_waitcnt lgkmcnt(2)
	v_mfma_f32_4x4x1_16b_f32 v[72:75], v140, v208, v[72:75]
	v_mfma_f32_4x4x1_16b_f32 v[44:47], v140, v250, v[44:47]
	v_mfma_f32_4x4x1_16b_f32 v[52:55], v151, v152, v[52:55]
	ds_read_b128 v[148:151], v139 offset:816
	v_mfma_f32_4x4x1_16b_f32 v[60:63], v141, v208, v[60:63]
	v_mfma_f32_4x4x1_16b_f32 v[32:35], v141, v250, v[32:35]
	s_waitcnt lgkmcnt(2)
	v_mfma_f32_4x4x1_16b_f32 v[44:47], v130, v152, v[44:47]
	v_mfma_f32_4x4x1_16b_f32 v[56:59], v142, v208, v[56:59]
	v_mfma_f32_4x4x1_16b_f32 v[24:27], v142, v250, v[24:27]
	v_mfma_f32_4x4x1_16b_f32 v[32:35], v131, v152, v[32:35]
	v_mfma_f32_4x4x1_16b_f32 v[48:51], v143, v208, v[48:51]
	v_mfma_f32_4x4x1_16b_f32 v[16:19], v143, v250, v[16:19]
	v_mfma_f32_4x4x1_16b_f32 v[24:27], v132, v152, v[24:27]
	s_waitcnt lgkmcnt(1)
	v_mfma_f32_4x4x1_16b_f32 v[40:43], v144, v208, v[40:43]
	v_mfma_f32_4x4x1_16b_f32 v[12:15], v144, v250, v[12:15]
	v_mfma_f32_4x4x1_16b_f32 v[16:19], v133, v152, v[16:19]
	v_mfma_f32_4x4x1_16b_f32 v[36:39], v145, v208, v[36:39]
	v_mfma_f32_4x4x1_16b_f32 v[8:11], v145, v250, v[8:11]
	s_waitcnt lgkmcnt(0)
	v_mfma_f32_4x4x1_16b_f32 v[12:15], v148, v152, v[12:15]
	v_mfma_f32_4x4x1_16b_f32 v[28:31], v146, v208, v[28:31]
	v_mfma_f32_4x4x1_16b_f32 v[4:7], v146, v250, v[4:7]
	v_mfma_f32_4x4x1_16b_f32 v[8:11], v149, v152, v[8:11]
	v_mfma_f32_4x4x1_16b_f32 v[20:23], v147, v208, v[20:23]
	v_mfma_f32_4x4x1_16b_f32 v[0:3], v147, v250, v[0:3]
	v_mfma_f32_4x4x1_16b_f32 v[4:7], v150, v152, v[4:7]
	s_nop 0
	v_mfma_f32_4x4x1_16b_f32 v[0:3], v151, v152, v[0:3]
	s_add_i32 s23, s23, 1
	s_cmp_eq_u32 s23, 8
	s_cbranch_scc0 .Lm0_sub
; template <int MODE> __device__ __forceinline__ void rwkv_item(const Params& P, int e, int c, int h, LAS float* slab, int lane) {
;     ...
;     if (MODE == 0) {
; #pragma unroll
;         for (int q = 0; q < 16; ++q) {
;             *(f32x4*)(MCM + rowoff + 4 * q) = (f32x4){S2[2 * q].x, S2[2 * q].y, S2[2 * q + 1].x, S2[2 * q + 1].y};
;             *(f32x4*)(MCC + rowoff + 4 * q) = (f32x4){C2[2 * q].x, C2[2 * q].y, C2[2 * q + 1].x, C2[2 * q + 1].y};
;         }
;     }
; template <int MODE> __device__ __forceinline__ void stage_rwkv_scan(const Params& P, int e, LAS unsigned char* lds) {
;     ...
;     for (int it = gw; it < RNCH * 8; it += ngw) rwkv_item<MODE>(P, e, it >> 3, it & 7, slab, lane);
	ds_write_b32 v129, v137
	v_mov_b32_e32 v233, s21
	s_waitcnt lgkmcnt(0)
	ds_read_b128 v[214:217], v233
	ds_read_b128 v[234:237], v233 offset:16
	ds_read_b128 v[238:241], v233 offset:32
	ds_read_b128 v[242:245], v233 offset:48
	s_waitcnt lgkmcnt(3)
	v_pk_mul_f32 v[112:113], v[112:113], v[214:215]
	v_pk_mul_f32 v[114:115], v[114:115], v[216:217]
	v_pk_mul_f32 v[124:125], v[124:125], v[214:215]
	v_pk_mul_f32 v[126:127], v[126:127], v[216:217]
	s_waitcnt lgkmcnt(2)
	v_pk_mul_f32 v[104:105], v[104:105], v[234:235]
	v_pk_mul_f32 v[106:107], v[106:107], v[236:237]
	v_pk_mul_f32 v[120:121], v[120:121], v[234:235]
	v_pk_mul_f32 v[122:123], v[122:123], v[236:237]
	s_waitcnt lgkmcnt(1)
	v_pk_mul_f32 v[92:93], v[92:93], v[238:239]
	v_pk_mul_f32 v[94:95], v[94:95], v[240:241]
	v_pk_mul_f32 v[116:117], v[116:117], v[238:239]
	v_pk_mul_f32 v[118:119], v[118:119], v[240:241]
	s_waitcnt lgkmcnt(0)
	v_pk_mul_f32 v[76:77], v[76:77], v[242:243]
	v_pk_mul_f32 v[78:79], v[78:79], v[244:245]
	v_pk_mul_f32 v[108:109], v[108:109], v[242:243]
	v_pk_mul_f32 v[110:111], v[110:111], v[244:245]
	ds_read_b128 v[214:217], v233 offset:64
	ds_read_b128 v[234:237], v233 offset:80
	ds_read_b128 v[238:241], v233 offset:96
	ds_read_b128 v[242:245], v233 offset:112
	s_waitcnt lgkmcnt(3)
	v_pk_mul_f32 v[64:65], v[64:65], v[214:215]
	v_pk_mul_f32 v[66:67], v[66:67], v[216:217]
	v_pk_mul_f32 v[96:97], v[96:97], v[214:215]
	v_pk_mul_f32 v[98:99], v[98:99], v[216:217]
	s_waitcnt lgkmcnt(2)
	v_pk_mul_f32 v[100:101], v[100:101], v[234:235]
	v_pk_mul_f32 v[102:103], v[102:103], v[236:237]
	v_pk_mul_f32 v[80:81], v[80:81], v[234:235]
	v_pk_mul_f32 v[82:83], v[82:83], v[236:237]
	s_waitcnt lgkmcnt(1)
	v_pk_mul_f32 v[88:89], v[88:89], v[238:239]
	v_pk_mul_f32 v[90:91], v[90:91], v[240:241]
	v_pk_mul_f32 v[68:69], v[68:69], v[238:239]
	v_pk_mul_f32 v[70:71], v[70:71], v[240:241]
	s_waitcnt lgkmcnt(0)
	v_pk_mul_f32 v[84:85], v[84:85], v[242:243]
	v_pk_mul_f32 v[86:87], v[86:87], v[244:245]
	v_pk_mul_f32 v[52:53], v[52:53], v[242:243]
	v_pk_mul_f32 v[54:55], v[54:55], v[244:245]
	ds_read_b128 v[214:217], v233 offset:128
	ds_read_b128 v[234:237], v233 offset:144
	ds_read_b128 v[238:241], v233 offset:160
	ds_read_b128 v[242:245], v233 offset:176
	s_waitcnt lgkmcnt(3)
	v_pk_mul_f32 v[72:73], v[72:73], v[214:215]
	v_pk_mul_f32 v[74:75], v[74:75], v[216:217]
	v_pk_mul_f32 v[44:45], v[44:45], v[214:215]
	v_pk_mul_f32 v[46:47], v[46:47], v[216:217]
	s_waitcnt lgkmcnt(2)
	v_pk_mul_f32 v[60:61], v[60:61], v[234:235]
	v_pk_mul_f32 v[62:63], v[62:63], v[236:237]
	v_pk_mul_f32 v[32:33], v[32:33], v[234:235]
	v_pk_mul_f32 v[34:35], v[34:35], v[236:237]
	s_waitcnt lgkmcnt(1)
	v_pk_mul_f32 v[56:57], v[56:57], v[238:239]
	v_pk_mul_f32 v[58:59], v[58:59], v[240:241]
	v_pk_mul_f32 v[24:25], v[24:25], v[238:239]
	v_pk_mul_f32 v[26:27], v[26:27], v[240:241]
	s_waitcnt lgkmcnt(0)
	v_pk_mul_f32 v[48:49], v[48:49], v[242:243]
	v_pk_mul_f32 v[50:51], v[50:51], v[244:245]
	v_pk_mul_f32 v[16:17], v[16:17], v[242:243]
	v_pk_mul_f32 v[18:19], v[18:19], v[244:245]
	ds_read_b128 v[214:217], v233 offset:192
	ds_read_b128 v[234:237], v233 offset:208
	ds_read_b128 v[238:241], v233 offset:224
	ds_read_b128 v[242:245], v233 offset:240
	s_waitcnt lgkmcnt(3)
	v_pk_mul_f32 v[40:41], v[40:41], v[214:215]
	v_pk_mul_f32 v[42:43], v[42:43], v[216:217]
	v_pk_mul_f32 v[12:13], v[12:13], v[214:215]
	v_pk_mul_f32 v[14:15], v[14:15], v[216:217]
	s_waitcnt lgkmcnt(2)
	v_pk_mul_f32 v[36:37], v[36:37], v[234:235]
	v_pk_mul_f32 v[38:39], v[38:39], v[236:237]
	v_pk_mul_f32 v[8:9], v[8:9], v[234:235]
	v_pk_mul_f32 v[10:11], v[10:11], v[236:237]
	s_waitcnt lgkmcnt(1)
	v_pk_mul_f32 v[28:29], v[28:29], v[238:239]
	v_pk_mul_f32 v[30:31], v[30:31], v[240:241]
	v_pk_mul_f32 v[4:5], v[4:5], v[238:239]
	v_pk_mul_f32 v[6:7], v[6:7], v[240:241]
	s_waitcnt lgkmcnt(0)
	v_pk_mul_f32 v[20:21], v[20:21], v[242:243]
	v_pk_mul_f32 v[22:23], v[22:23], v[244:245]
	v_pk_mul_f32 v[0:1], v[0:1], v[242:243]
	v_pk_mul_f32 v[2:3], v[2:3], v[244:245]
	s_lshl_b32 s2, s20, 6
	v_or_b32_e32 v204, s2, v128
	v_lshlrev_b32_e32 v204, 8, v204
	s_add_i32 s20, s20, s58
	global_store_dwordx4 v204, v[112:115], s[18:19]
	global_store_dwordx4 v204, v[124:127], s[8:9]
	global_store_dwordx4 v204, v[104:107], s[18:19] offset:16
	global_store_dwordx4 v204, v[120:123], s[8:9] offset:16
	global_store_dwordx4 v204, v[92:95], s[18:19] offset:32
	global_store_dwordx4 v204, v[116:119], s[8:9] offset:32
	global_store_dwordx4 v204, v[76:79], s[18:19] offset:48
	global_store_dwordx4 v204, v[108:111], s[8:9] offset:48
	global_store_dwordx4 v204, v[64:67], s[18:19] offset:64
	global_store_dwordx4 v204, v[96:99], s[8:9] offset:64
	global_store_dwordx4 v204, v[100:103], s[18:19] offset:80
	global_store_dwordx4 v204, v[80:83], s[8:9] offset:80
	global_store_dwordx4 v204, v[88:91], s[18:19] offset:96
	global_store_dwordx4 v204, v[68:71], s[8:9] offset:96
	global_store_dwordx4 v204, v[84:87], s[18:19] offset:112
	global_store_dwordx4 v204, v[52:55], s[8:9] offset:112
	global_store_dwordx4 v204, v[72:75], s[18:19] offset:128
	global_store_dwordx4 v204, v[44:47], s[8:9] offset:128
	global_store_dwordx4 v204, v[60:63], s[18:19] offset:144
	global_store_dwordx4 v204, v[32:35], s[8:9] offset:144
	global_store_dwordx4 v204, v[56:59], s[18:19] offset:160
	global_store_dwordx4 v204, v[24:27], s[8:9] offset:160
	global_store_dwordx4 v204, v[48:51], s[18:19] offset:176
	global_store_dwordx4 v204, v[16:19], s[8:9] offset:176
	global_store_dwordx4 v204, v[40:43], s[18:19] offset:192
	global_store_dwordx4 v204, v[12:15], s[8:9] offset:192
	global_store_dwordx4 v204, v[36:39], s[18:19] offset:208
	global_store_dwordx4 v204, v[8:11], s[8:9] offset:208
	global_store_dwordx4 v204, v[28:31], s[18:19] offset:224
	global_store_dwordx4 v204, v[4:7], s[8:9] offset:224
	global_store_dwordx4 v204, v[20:23], s[18:19] offset:240
	global_store_dwordx4 v204, v[0:3], s[8:9] offset:240
	s_cmpk_gt_i32 s20, 0x7ff
	s_cbranch_scc0 .LBB0_262
	v_mov_b32_e32 v210, 1
	v_mov_b64_e32 v[244:245], 0x180
	v_mov_b64_e32 v[246:247], 0x80
	v_mov_b64_e32 v[248:249], 0x7f
